# layer-1 norm1 ctx rows: the 44 split-K partial loads issued together instead of one per wait (same summation order)
# speedup vs baseline: 1.0534x; 1.0104x over previous
.LBB0_155:
	s_ashr_i32 s5, s4, 31
	s_lshl_b64 s[6:7], s[4:5], 12
	s_waitcnt lgkmcnt(0)
	s_add_u32 s0, s0, s6
	s_addc_u32 s1, s1, s7
	v_lshlrev_b32_e32 v168, 4, v88
	v_lshl_add_u64 v[0:1], s[0:1], 0, v[168:169]
	flat_load_dwordx4 v[12:15], v[0:1]
	flat_load_dwordx4 v[8:11], v[0:1] offset:1024
	flat_load_dwordx4 v[4:7], v[0:1] offset:2048
	s_nop 0
	flat_load_dwordx4 v[0:3], v[0:1] offset:3072
	v_readlane_b32 s0, v253, 5
	v_readlane_b32 s1, v253, 6
	s_andn2_b64 vcc, exec, s[0:1]
	s_cbranch_vccnz .LBB0_152
	s_lshl_b64 s[0:1], s[4:5], 10
	s_lshl_b64 s[0:1], s[0:1], 2
	s_add_u32 s6, s10, s0
	s_addc_u32 s7, s11, s1
	global_load_dwordx4 v[16:19], v168, s[6:7]
	global_load_dwordx4 v[50:53], v168, s[6:7] offset:1024
	global_load_dwordx4 v[54:57], v168, s[6:7] offset:2048
	global_load_dwordx4 v[58:61], v168, s[6:7] offset:3072
	s_add_u32 s8, s6, 0x200000
	s_addc_u32 s9, s7, 0
	global_load_dwordx4 v[72:75], v168, s[8:9]
	global_load_dwordx4 v[76:79], v68, s[8:9]
	global_load_dwordx4 v[80:83], v69, s[8:9]
	global_load_dwordx4 v[84:87], v70, s[8:9]
	s_add_u32 s8, s6, 0x400000
	s_addc_u32 s9, s7, 0
	global_load_dwordx4 v[92:95], v168, s[8:9]
	global_load_dwordx4 v[96:99], v68, s[8:9]
	global_load_dwordx4 v[104:107], v69, s[8:9]
	global_load_dwordx4 v[108:111], v70, s[8:9]
	s_add_u32 s8, s6, 0x600000
	s_addc_u32 s9, s7, 0
	global_load_dwordx4 v[112:115], v168, s[8:9]
	global_load_dwordx4 v[116:119], v68, s[8:9]
	global_load_dwordx4 v[120:123], v69, s[8:9]
	global_load_dwordx4 v[124:127], v70, s[8:9]
	s_add_u32 s8, s6, 0x800000
	s_addc_u32 s9, s7, 0
	global_load_dwordx4 v[128:131], v168, s[8:9]
	global_load_dwordx4 v[132:135], v68, s[8:9]
	global_load_dwordx4 v[136:139], v69, s[8:9]
	global_load_dwordx4 v[140:143], v70, s[8:9]
	s_add_u32 s8, s6, 0xa00000
	s_addc_u32 s9, s7, 0
	global_load_dwordx4 v[144:147], v168, s[8:9]
	global_load_dwordx4 v[148:151], v68, s[8:9]
	global_load_dwordx4 v[152:155], v69, s[8:9]
	global_load_dwordx4 v[156:159], v70, s[8:9]
	s_add_u32 s8, s6, 0xc00000
	s_addc_u32 s9, s7, 0
	global_load_dwordx4 v[160:163], v168, s[8:9]
	global_load_dwordx4 v[164:167], v68, s[8:9]
	global_load_dwordx4 v[172:175], v69, s[8:9]
	global_load_dwordx4 v[176:179], v70, s[8:9]
	s_add_u32 s8, s6, 0xe00000
	s_addc_u32 s9, s7, 0
	global_load_dwordx4 v[180:183], v168, s[8:9]
	global_load_dwordx4 v[184:187], v68, s[8:9]
	global_load_dwordx4 v[188:191], v69, s[8:9]
	global_load_dwordx4 v[192:195], v70, s[8:9]
	s_add_u32 s8, s6, 0x1000000
	s_addc_u32 s9, s7, 0
	global_load_dwordx4 v[196:199], v168, s[8:9]
	global_load_dwordx4 v[200:203], v68, s[8:9]
	global_load_dwordx4 v[212:215], v69, s[8:9]
	global_load_dwordx4 v[216:219], v70, s[8:9]
	s_add_u32 s8, s6, 0x1200000
	s_addc_u32 s9, s7, 0
	global_load_dwordx4 v[220:223], v168, s[8:9]
	global_load_dwordx4 v[224:227], v68, s[8:9]
	global_load_dwordx4 v[228:231], v69, s[8:9]
	global_load_dwordx4 v[232:235], v70, s[8:9]
	s_add_u32 s8, s6, 0x1400000
	s_addc_u32 s9, s7, 0
	global_load_dwordx4 v[236:239], v168, s[8:9]
	global_load_dwordx4 v[240:243], v68, s[8:9]
	global_load_dwordx4 v[244:247], v69, s[8:9]
	global_load_dwordx4 v[248:251], v70, s[8:9]
	s_waitcnt vmcnt(0) lgkmcnt(0)
	v_pk_add_f32 v[16:17], v[16:17], 0 op_sel_hi:[1,0]
	v_pk_add_f32 v[18:19], v[18:19], 0 op_sel_hi:[1,0]
	v_pk_add_f32 v[50:51], v[50:51], 0 op_sel_hi:[1,0]
	v_pk_add_f32 v[52:53], v[52:53], 0 op_sel_hi:[1,0]
	v_pk_add_f32 v[54:55], v[54:55], 0 op_sel_hi:[1,0]
	v_pk_add_f32 v[56:57], v[56:57], 0 op_sel_hi:[1,0]
	v_pk_add_f32 v[58:59], v[58:59], 0 op_sel_hi:[1,0]
	v_pk_add_f32 v[60:61], v[60:61], 0 op_sel_hi:[1,0]
	v_pk_add_f32 v[16:17], v[16:17], v[72:73]
	v_pk_add_f32 v[18:19], v[18:19], v[74:75]
	v_pk_add_f32 v[50:51], v[50:51], v[76:77]
	v_pk_add_f32 v[52:53], v[52:53], v[78:79]
	v_pk_add_f32 v[54:55], v[54:55], v[80:81]
	v_pk_add_f32 v[56:57], v[56:57], v[82:83]
	v_pk_add_f32 v[58:59], v[58:59], v[84:85]
	v_pk_add_f32 v[60:61], v[60:61], v[86:87]
	v_pk_add_f32 v[16:17], v[16:17], v[92:93]
	v_pk_add_f32 v[18:19], v[18:19], v[94:95]
	v_pk_add_f32 v[50:51], v[50:51], v[96:97]
	v_pk_add_f32 v[52:53], v[52:53], v[98:99]
	v_pk_add_f32 v[54:55], v[54:55], v[104:105]
	v_pk_add_f32 v[56:57], v[56:57], v[106:107]
	v_pk_add_f32 v[58:59], v[58:59], v[108:109]
	v_pk_add_f32 v[60:61], v[60:61], v[110:111]
	v_pk_add_f32 v[16:17], v[16:17], v[112:113]
	v_pk_add_f32 v[18:19], v[18:19], v[114:115]
	v_pk_add_f32 v[50:51], v[50:51], v[116:117]
	v_pk_add_f32 v[52:53], v[52:53], v[118:119]
	v_pk_add_f32 v[54:55], v[54:55], v[120:121]
	v_pk_add_f32 v[56:57], v[56:57], v[122:123]
	v_pk_add_f32 v[58:59], v[58:59], v[124:125]
	v_pk_add_f32 v[60:61], v[60:61], v[126:127]
	v_pk_add_f32 v[16:17], v[16:17], v[128:129]
	v_pk_add_f32 v[18:19], v[18:19], v[130:131]
	v_pk_add_f32 v[50:51], v[50:51], v[132:133]
	v_pk_add_f32 v[52:53], v[52:53], v[134:135]
	v_pk_add_f32 v[54:55], v[54:55], v[136:137]
	v_pk_add_f32 v[56:57], v[56:57], v[138:139]
	v_pk_add_f32 v[58:59], v[58:59], v[140:141]
	v_pk_add_f32 v[60:61], v[60:61], v[142:143]
	v_pk_add_f32 v[16:17], v[16:17], v[144:145]
	v_pk_add_f32 v[18:19], v[18:19], v[146:147]
	v_pk_add_f32 v[50:51], v[50:51], v[148:149]
	v_pk_add_f32 v[52:53], v[52:53], v[150:151]
	v_pk_add_f32 v[54:55], v[54:55], v[152:153]
	v_pk_add_f32 v[56:57], v[56:57], v[154:155]
	v_pk_add_f32 v[58:59], v[58:59], v[156:157]
	v_pk_add_f32 v[60:61], v[60:61], v[158:159]
	v_pk_add_f32 v[16:17], v[16:17], v[160:161]
	v_pk_add_f32 v[18:19], v[18:19], v[162:163]
	v_pk_add_f32 v[50:51], v[50:51], v[164:165]
	v_pk_add_f32 v[52:53], v[52:53], v[166:167]
	v_pk_add_f32 v[54:55], v[54:55], v[172:173]
	v_pk_add_f32 v[56:57], v[56:57], v[174:175]
	v_pk_add_f32 v[58:59], v[58:59], v[176:177]
	v_pk_add_f32 v[60:61], v[60:61], v[178:179]
	v_pk_add_f32 v[16:17], v[16:17], v[180:181]
	v_pk_add_f32 v[18:19], v[18:19], v[182:183]
	v_pk_add_f32 v[50:51], v[50:51], v[184:185]
	v_pk_add_f32 v[52:53], v[52:53], v[186:187]
	v_pk_add_f32 v[54:55], v[54:55], v[188:189]
	v_pk_add_f32 v[56:57], v[56:57], v[190:191]
	v_pk_add_f32 v[58:59], v[58:59], v[192:193]
	v_pk_add_f32 v[60:61], v[60:61], v[194:195]
	v_pk_add_f32 v[16:17], v[16:17], v[196:197]
	v_pk_add_f32 v[18:19], v[18:19], v[198:199]
	v_pk_add_f32 v[50:51], v[50:51], v[200:201]
	v_pk_add_f32 v[52:53], v[52:53], v[202:203]
	v_pk_add_f32 v[54:55], v[54:55], v[212:213]
	v_pk_add_f32 v[56:57], v[56:57], v[214:215]
	v_pk_add_f32 v[58:59], v[58:59], v[216:217]
	v_pk_add_f32 v[60:61], v[60:61], v[218:219]
	v_pk_add_f32 v[16:17], v[16:17], v[220:221]
	v_pk_add_f32 v[18:19], v[18:19], v[222:223]
	v_pk_add_f32 v[50:51], v[50:51], v[224:225]
	v_pk_add_f32 v[52:53], v[52:53], v[226:227]
	v_pk_add_f32 v[54:55], v[54:55], v[228:229]
	v_pk_add_f32 v[56:57], v[56:57], v[230:231]
	v_pk_add_f32 v[58:59], v[58:59], v[232:233]
	v_pk_add_f32 v[60:61], v[60:61], v[234:235]
	v_pk_add_f32 v[16:17], v[16:17], v[236:237]
	v_pk_add_f32 v[18:19], v[18:19], v[238:239]
	v_pk_add_f32 v[50:51], v[50:51], v[240:241]
	v_pk_add_f32 v[52:53], v[52:53], v[242:243]
	v_pk_add_f32 v[54:55], v[54:55], v[244:245]
	v_pk_add_f32 v[56:57], v[56:57], v[246:247]
	v_pk_add_f32 v[58:59], v[58:59], v[248:249]
	v_pk_add_f32 v[60:61], v[60:61], v[250:251]
	flat_load_dwordx4 v[72:75], v[38:39]
	flat_load_dwordx4 v[76:79], v[40:41]
	flat_load_dwordx4 v[80:83], v[42:43]
	flat_load_dwordx4 v[84:87], v[44:45]
	v_lshl_add_u64 v[100:101], v[46:47], 0, s[0:1]
	s_waitcnt vmcnt(0) lgkmcnt(0)
	v_pk_fma_f32 v[12:13], v[16:17], v[72:73], v[12:13]
	v_pk_fma_f32 v[14:15], v[18:19], v[74:75], v[14:15]
	v_pk_fma_f32 v[8:9], v[50:51], v[76:77], v[8:9]
	v_pk_fma_f32 v[10:11], v[52:53], v[78:79], v[10:11]
	v_pk_fma_f32 v[4:5], v[54:55], v[80:81], v[4:5]
	v_pk_fma_f32 v[6:7], v[56:57], v[82:83], v[6:7]
	v_pk_fma_f32 v[0:1], v[58:59], v[84:85], v[0:1]
	v_pk_fma_f32 v[2:3], v[60:61], v[86:87], v[2:3]
	flat_store_dwordx4 v[100:101], v[12:15]
	flat_store_dwordx4 v[100:101], v[8:11] offset:1024
	flat_store_dwordx4 v[100:101], v[4:7] offset:2048
	flat_store_dwordx4 v[100:101], v[0:3] offset:3072
	s_branch .LBB0_152
